# P4 loops unrolled by four (four items' loads in flight per wave)
# speedup vs baseline: 1.0070x; 1.0014x over previous
; DEVINL float bflo(unsigned u) { return __uint_as_float(u << 16); }
; DEVINL float bfhi(unsigned u) { return __uint_as_float(u & 0xffff0000u); }
; DEVINL void phase4(const Params& p) {
;     ...
;   for (int u = gw; u < T_ * 4; u += nw) {
;     const long t = u >> 2; const int h = u & 3;
;     const int c = h * 256 + lane * 4;
;     float4 o;
;     {
;       uint2 of = *(const uint2*)((const u16*)(ws + O_OSUM) + t * 1024 + c);
;       uint2 ob = *(const uint2*)((const u16*)(ws + O_OSUM) + (long)T_ * 1024 + t * 1024 + c);
;       o.x = bflo(of.x) + bflo(ob.x); o.y = bfhi(of.x) + bfhi(ob.x);
;       o.z = bflo(of.y) + bflo(ob.y); o.w = bfhi(of.y) + bfhi(ob.y);
;     }
;     float ss = o.x * o.x + o.y * o.y + o.z * o.z + o.w * o.w;
;     ss = allred64(ss);
;     const float rstd = rsqrtf(ss * (1.f / 256.f) + 1e-5f);
;     float4 ng = *(const float4*)(p.gla_norm_g + c);
;     uint2 gg = *(const uint2*)(cols + t * NCP + C_G + c);
.LBB0_550:
	s_or_b64 exec, exec, s[0:1]
	v_mov_b32_e32 v4, v189
	s_waitcnt lgkmcnt(0)
	s_barrier
	s_lshl_b32 s52, s2, 3
	v_ashrrev_i32_e32 v3, 6, v4
	v_add_u32_e32 v2, s52, v3
	s_mov_b32 s0, 0x8000
	s_lshl_b32 s60, s94, 3
	v_cmp_gt_i32_e32 vcc, s0, v2
	s_and_saveexec_b64 s[12:13], vcc
	s_cbranch_execz .LBB0_555
	s_add_u32 s14, s92, 0x1000000
	s_addc_u32 s15, s93, 0
	v_and_b32_e32 v5, 63, v4
	s_add_u32 s16, s92, 0xf400000
	v_lshlrev_b32_e32 v0, 8, v3
	v_lshlrev_b32_e32 v6, 2, v5
	s_addc_u32 s17, s93, 0
	v_lshl_add_u32 v7, s2, 11, v0
	s_lshl_b32 s3, s94, 11
	s_mov_b64 s[18:19], 0
	s_movk_i32 s20, 0x300
	v_mov_b32_e32 v1, 0
	s_movk_i32 s21, 0x4c00
	s_mov_b32 s22, 0x4c01000
	v_mov_b32_e32 v8, 0x3727c5ac
	v_mov_b32_e32 v9, 0x3b800000
	s_mov_b32 s23, 0x800000
	s_movk_i32 s24, 0x7fff
	v_mov_b32_e32 v10, v2
	v_mov_b32_e32 v53, v1
	v_mov_b32_e32 v105, v1
	v_mov_b32_e32 v201, v1
.LBB0_552:
	v_ashrrev_i32_e32 v16, 2, v10
	v_ashrrev_i32_e32 v17, 31, v16
	v_lshlrev_b64 v[18:19], 11, v[16:17]
	v_and_or_b32 v11, v7, s20, v6
	v_lshl_add_u64 v[20:21], s[92:93], 0, v[18:19]
	v_add_u32_e32 v10, s60, v10
	v_lshlrev_b32_e32 v0, 1, v11
	v_lshl_add_u64 v[22:23], s[14:15], 0, v[18:19]
	v_mad_i64_i32 v[16:17], s[0:1], v16, s21, v[20:21]
	v_lshlrev_b32_e32 v11, 2, v11
	v_cmp_lt_i32_e32 vcc, s24, v10
	v_lshl_add_u64 v[24:25], v[20:21], 0, v[0:1]
	v_lshl_add_u64 v[22:23], v[22:23], 0, v[0:1]
	v_lshl_add_u64 v[16:17], v[16:17], 0, v[0:1]
	global_load_dwordx4 v[12:15], v11, s[88:89]
	s_or_b64 s[18:19], vcc, s[18:19]
	global_load_dwordx2 v[20:21], v[24:25], off
	s_nop 0
	global_load_dwordx2 v[22:23], v[22:23], off
	v_add_co_u32_e32 v16, vcc, s22, v16
	v_lshl_add_u64 v[18:19], s[16:17], 0, v[18:19]
	s_nop 0
	v_addc_co_u32_e32 v17, vcc, 0, v17, vcc
	global_load_dwordx2 v[16:17], v[16:17], off
	v_lshl_add_u64 v[18:19], v[18:19], 0, v[0:1]
	v_mov_b32_e32 v32, v1
	v_mov_b32_e32 v33, v1
	v_add_u32_e32 v7, s3, v7
	v_ashrrev_i32_e32 v68, 2, v10
	v_ashrrev_i32_e32 v69, 31, v68
	v_lshlrev_b64 v[70:71], 11, v[68:69]
	v_and_or_b32 v63, v7, s20, v6
	v_lshl_add_u64 v[72:73], s[92:93], 0, v[70:71]
	v_add_u32_e32 v10, s60, v10
	v_lshlrev_b32_e32 v52, 1, v63
	v_lshl_add_u64 v[74:75], s[14:15], 0, v[70:71]
	v_mad_i64_i32 v[68:69], s[0:1], v68, s21, v[72:73]
	v_lshlrev_b32_e32 v63, 2, v63
	v_cmp_lt_i32_e32 vcc, s24, v10
	v_lshl_add_u64 v[76:77], v[72:73], 0, v[52:53]
	v_lshl_add_u64 v[74:75], v[74:75], 0, v[52:53]
	v_lshl_add_u64 v[68:69], v[68:69], 0, v[52:53]
	global_load_dwordx4 v[64:67], v63, s[88:89]
	s_or_b64 s[18:19], vcc, s[18:19]
	global_load_dwordx2 v[72:73], v[76:77], off
	s_nop 0
	global_load_dwordx2 v[74:75], v[74:75], off
	v_add_co_u32_e32 v68, vcc, s22, v68
	v_lshl_add_u64 v[70:71], s[16:17], 0, v[70:71]
	s_nop 0
	v_addc_co_u32_e32 v69, vcc, 0, v69, vcc
	global_load_dwordx2 v[68:69], v[68:69], off
	v_lshl_add_u64 v[70:71], v[70:71], 0, v[52:53]
	v_mov_b32_e32 v84, v53
	v_mov_b32_e32 v85, v53
	v_add_u32_e32 v7, s3, v7
	v_ashrrev_i32_e32 v120, 2, v10
	v_ashrrev_i32_e32 v121, 31, v120
	v_lshlrev_b64 v[122:123], 11, v[120:121]
	v_and_or_b32 v115, v7, s20, v6
	v_lshl_add_u64 v[124:125], s[92:93], 0, v[122:123]
	v_add_u32_e32 v10, s60, v10
	v_lshlrev_b32_e32 v104, 1, v115
	v_lshl_add_u64 v[126:127], s[14:15], 0, v[122:123]
	v_mad_i64_i32 v[120:121], s[0:1], v120, s21, v[124:125]
	v_lshlrev_b32_e32 v115, 2, v115
	v_cmp_lt_i32_e32 vcc, s24, v10
	v_lshl_add_u64 v[128:129], v[124:125], 0, v[104:105]
	v_lshl_add_u64 v[126:127], v[126:127], 0, v[104:105]
	v_lshl_add_u64 v[120:121], v[120:121], 0, v[104:105]
	global_load_dwordx4 v[116:119], v115, s[88:89]
	s_or_b64 s[18:19], vcc, s[18:19]
	global_load_dwordx2 v[124:125], v[128:129], off
	s_nop 0
	global_load_dwordx2 v[126:127], v[126:127], off
	v_add_co_u32_e32 v120, vcc, s22, v120
	v_lshl_add_u64 v[122:123], s[16:17], 0, v[122:123]
	s_nop 0
	v_addc_co_u32_e32 v121, vcc, 0, v121, vcc
	global_load_dwordx2 v[120:121], v[120:121], off
	v_lshl_add_u64 v[122:123], v[122:123], 0, v[104:105]
	v_mov_b32_e32 v136, v105
	v_mov_b32_e32 v137, v105
	v_add_u32_e32 v7, s3, v7
	v_ashrrev_i32_e32 v216, 2, v10
	v_ashrrev_i32_e32 v217, 31, v216
	v_lshlrev_b64 v[218:219], 11, v[216:217]
	v_and_or_b32 v211, v7, s20, v6
	v_lshl_add_u64 v[220:221], s[92:93], 0, v[218:219]
	v_add_u32_e32 v10, s60, v10
	v_lshlrev_b32_e32 v200, 1, v211
	v_lshl_add_u64 v[222:223], s[14:15], 0, v[218:219]
	v_mad_i64_i32 v[216:217], s[0:1], v216, s21, v[220:221]
	v_lshlrev_b32_e32 v211, 2, v211
	v_cmp_lt_i32_e32 vcc, s24, v10
	v_lshl_add_u64 v[224:225], v[220:221], 0, v[200:201]
	v_lshl_add_u64 v[222:223], v[222:223], 0, v[200:201]
	v_lshl_add_u64 v[216:217], v[216:217], 0, v[200:201]
	global_load_dwordx4 v[212:215], v211, s[88:89]
	s_or_b64 s[18:19], vcc, s[18:19]
	global_load_dwordx2 v[220:221], v[224:225], off
	s_nop 0
	global_load_dwordx2 v[222:223], v[222:223], off
	v_add_co_u32_e32 v216, vcc, s22, v216
	v_lshl_add_u64 v[218:219], s[16:17], 0, v[218:219]
	s_nop 0
	v_addc_co_u32_e32 v217, vcc, 0, v217, vcc
	global_load_dwordx2 v[216:217], v[216:217], off
	v_lshl_add_u64 v[218:219], v[218:219], 0, v[200:201]
	v_mov_b32_e32 v232, v201
	v_mov_b32_e32 v233, v201
	v_add_u32_e32 v7, s3, v7
	s_waitcnt vmcnt(14)
	v_lshlrev_b32_e32 v24, 16, v20
	s_waitcnt vmcnt(13)
	v_lshlrev_b32_e32 v26, 16, v22
	v_and_b32_e32 v25, 0xffff0000, v20
	v_and_b32_e32 v27, 0xffff0000, v22
	v_lshlrev_b32_e32 v20, 16, v21
	v_lshlrev_b32_e32 v22, 16, v23
	v_and_b32_e32 v21, 0xffff0000, v21
	v_and_b32_e32 v23, 0xffff0000, v23
	v_pk_add_f32 v[20:21], v[20:21], v[22:23]
	v_pk_add_f32 v[22:23], v[24:25], v[26:27]
	s_waitcnt vmcnt(12)
; DEVINL float bflo(unsigned u) { return __uint_as_float(u << 16); }
; DEVINL float bfhi(unsigned u) { return __uint_as_float(u & 0xffff0000u); }
; DEVINL float sigm(float x) { return 1.f / (1.f + __expf(-x)); }
; DEVINL void phase4(const Params& p) {
;     ...
;     float ss = o.x * o.x + o.y * o.y + o.z * o.z + o.w * o.w;
;     ss = allred64(ss);
;     const float rstd = rsqrtf(ss * (1.f / 256.f) + 1e-5f);
;     float4 ng = *(const float4*)(p.gla_norm_g + c);
;     uint2 gg = *(const uint2*)(cols + t * NCP + C_G + c);
;     float g0 = bflo(gg.x), g1 = bfhi(gg.x), g2 = bflo(gg.y), g3 = bfhi(gg.y);
;     float y0 = o.x * rstd * ng.x * (g0 * sigm(g0));
;     float y1 = o.y * rstd * ng.y * (g1 * sigm(g1));
;     float y2 = o.z * rstd * ng.z * (g2 * sigm(g2));
;     float y3 = o.w * rstd * ng.w * (g3 * sigm(g3));
;     *(uint2*)((u16*)(ws + O_YGLA) + t * 1024 + c) = make_uint2(pk2(y0, y1), pk2(y2, y3));
;   }
	v_lshlrev_b32_e32 v24, 16, v16
	v_and_b32_e32 v25, 0xffff0000, v16
	v_pk_mul_f32 v[28:29], v[22:23], v[22:23]
	v_lshlrev_b32_e32 v16, 16, v17
	v_and_b32_e32 v17, 0xffff0000, v17
	v_pk_mul_f32 v[26:27], v[20:21], v[20:21]
	v_mul_f32_e32 v0, 0xbfb8aa3b, v24
	v_mul_f32_e32 v11, 0xbfb8aa3b, v25
	v_add_f32_e32 v30, v28, v29
	v_mul_f32_e32 v31, 0xbfb8aa3b, v16
	v_mul_f32_e32 v34, 0xbfb8aa3b, v17
	v_exp_f32_e32 v28, v0
	v_exp_f32_e32 v29, v11
	v_add_f32_e32 v0, v30, v26
	v_exp_f32_e32 v30, v31
	v_exp_f32_e32 v31, v34
	v_add_f32_e32 v0, v27, v0
	v_pk_add_f32 v[26:27], v[28:29], 1.0 op_sel_hi:[1,0]
	v_pk_add_f32 v[28:29], v[30:31], 1.0 op_sel_hi:[1,0]
	v_add_f32_dpp v0, v0, v0 quad_perm:[1,0,3,2] row_mask:0xf bank_mask:0xf bound_ctrl:1
	v_div_scale_f32 v11, s[0:1], v27, v27, 1.0
	s_nop 0
	v_add_f32_dpp v0, v0, v0 quad_perm:[2,3,0,1] row_mask:0xf bank_mask:0xf bound_ctrl:1
	v_div_scale_f32 v31, s[0:1], v26, v26, 1.0
	s_nop 0
	v_add_f32_dpp v0, v0, v0 row_half_mirror row_mask:0xf bank_mask:0xf bound_ctrl:1
	v_div_scale_f32 v35, s[6:7], v29, v29, 1.0
	s_nop 0
	v_add_f32_dpp v0, v0, v0 row_mirror row_mask:0xf bank_mask:0xf bound_ctrl:1
	v_div_scale_f32 v37, s[8:9], v28, v28, 1.0
	v_rcp_f32_e32 v39, v11
	v_mov_b32_dpp v32, v0 row_bcast:15 row_mask:0xa bank_mask:0xf
	v_rcp_f32_e32 v40, v31
	v_rcp_f32_e32 v41, v35
	v_rcp_f32_e32 v42, v37
	v_add_f32_e32 v0, v0, v32
	v_fma_f32 v32, -v11, v39, 1.0
	v_div_scale_f32 v30, vcc, 1.0, v27, 1.0
	v_mov_b32_dpp v33, v0 row_bcast:31 row_mask:0xc bank_mask:0xf
	v_add_f32_e32 v0, v0, v33
	v_fma_f32 v33, -v31, v40, 1.0
	v_readlane_b32 s10, v0, 63
	v_fma_f32 v0, -v35, v41, 1.0
	v_fma_f32 v43, -v37, v42, 1.0
	v_fmac_f32_e32 v39, v32, v39
	v_fma_f32 v32, s10, v9, v8
	v_div_scale_f32 v34, s[0:1], 1.0, v26, 1.0
	v_fmac_f32_e32 v40, v33, v40
	v_fmac_f32_e32 v41, v0, v41
	v_fmac_f32_e32 v42, v43, v42
	v_mul_f32_e32 v0, v30, v39
	v_mul_f32_e32 v43, 0x4b800000, v32
	v_cmp_gt_f32_e64 s[10:11], s23, v32
	v_div_scale_f32 v36, s[6:7], 1.0, v29, 1.0
	v_mul_f32_e32 v33, v34, v40
	v_fma_f32 v46, -v11, v0, v30
	v_cndmask_b32_e64 v32, v32, v43, s[10:11]
	v_div_scale_f32 v38, s[8:9], 1.0, v28, 1.0
	v_mul_f32_e32 v44, v36, v41
	v_fma_f32 v47, -v31, v33, v34
	v_fmac_f32_e32 v0, v46, v39
	v_rsq_f32_e32 v32, v32
	v_mul_f32_e32 v45, v38, v42
	v_fma_f32 v43, -v35, v44, v36
	v_fmac_f32_e32 v33, v47, v40
	v_fma_f32 v11, -v11, v0, v30
	v_fma_f32 v48, -v37, v45, v38
	v_fmac_f32_e32 v44, v43, v41
	v_fma_f32 v30, -v31, v33, v34
	v_div_fmas_f32 v0, v11, v39, v0
	s_mov_b64 vcc, s[0:1]
	v_fmac_f32_e32 v45, v48, v42
	v_fma_f32 v31, -v35, v44, v36
	v_div_fixup_f32 v27, v0, v27, 1.0
	v_div_fmas_f32 v0, v30, v40, v33
	s_mov_b64 vcc, s[6:7]
	v_fma_f32 v34, -v37, v45, v38
	v_div_fixup_f32 v26, v0, v26, 1.0
	v_mul_f32_e32 v0, 0x45800000, v32
	v_div_fmas_f32 v11, v31, v41, v44
	s_mov_b64 vcc, s[8:9]
	v_pk_mul_f32 v[24:25], v[26:27], v[24:25]
	v_cndmask_b32_e64 v0, v32, v0, s[10:11]
	v_div_fixup_f32 v27, v11, v29, 1.0
	v_div_fmas_f32 v11, v34, v42, v45
	v_pk_mul_f32 v[22:23], v[22:23], v[0:1] op_sel_hi:[1,0]
	v_pk_mul_f32 v[20:21], v[20:21], v[0:1] op_sel_hi:[1,0]
	v_div_fixup_f32 v26, v11, v28, 1.0
	v_pk_mul_f32 v[12:13], v[12:13], v[22:23]
	v_pk_mul_f32 v[14:15], v[14:15], v[20:21]
	v_pk_mul_f32 v[16:17], v[26:27], v[16:17]
	v_pk_mul_f32 v[12:13], v[12:13], v[24:25]
	v_pk_mul_f32 v[14:15], v[14:15], v[16:17]
	v_cvt_pk_bf16_f32 v12, v12, v13
	v_cvt_pk_bf16_f32 v13, v14, v15
	global_store_dwordx2 v[18:19], v[12:13], off
	s_waitcnt vmcnt(11)
	v_lshlrev_b32_e32 v76, 16, v72
	s_waitcnt vmcnt(10)
	v_lshlrev_b32_e32 v78, 16, v74
	v_and_b32_e32 v77, 0xffff0000, v72
	v_and_b32_e32 v79, 0xffff0000, v74
	v_lshlrev_b32_e32 v72, 16, v73
	v_lshlrev_b32_e32 v74, 16, v75
	v_and_b32_e32 v73, 0xffff0000, v73
	v_and_b32_e32 v75, 0xffff0000, v75
	v_pk_add_f32 v[72:73], v[72:73], v[74:75]
	v_pk_add_f32 v[74:75], v[76:77], v[78:79]
	s_waitcnt vmcnt(9)
	v_lshlrev_b32_e32 v76, 16, v68
	v_and_b32_e32 v77, 0xffff0000, v68
	v_pk_mul_f32 v[80:81], v[74:75], v[74:75]
	v_lshlrev_b32_e32 v68, 16, v69
	v_and_b32_e32 v69, 0xffff0000, v69
	v_pk_mul_f32 v[78:79], v[72:73], v[72:73]
	v_mul_f32_e32 v52, 0xbfb8aa3b, v76
	v_mul_f32_e32 v63, 0xbfb8aa3b, v77
	v_add_f32_e32 v82, v80, v81
	v_mul_f32_e32 v83, 0xbfb8aa3b, v68
	v_mul_f32_e32 v86, 0xbfb8aa3b, v69
	v_exp_f32_e32 v80, v52
	v_exp_f32_e32 v81, v63
	v_add_f32_e32 v52, v82, v78
	v_exp_f32_e32 v82, v83
	v_exp_f32_e32 v83, v86
	v_add_f32_e32 v52, v79, v52
	v_pk_add_f32 v[78:79], v[80:81], 1.0 op_sel_hi:[1,0]
	v_pk_add_f32 v[80:81], v[82:83], 1.0 op_sel_hi:[1,0]
	v_add_f32_dpp v52, v52, v52 quad_perm:[1,0,3,2] row_mask:0xf bank_mask:0xf bound_ctrl:1
	v_div_scale_f32 v63, s[0:1], v79, v79, 1.0
	s_nop 0
	v_add_f32_dpp v52, v52, v52 quad_perm:[2,3,0,1] row_mask:0xf bank_mask:0xf bound_ctrl:1
	v_div_scale_f32 v83, s[0:1], v78, v78, 1.0
	s_nop 0
	v_add_f32_dpp v52, v52, v52 row_half_mirror row_mask:0xf bank_mask:0xf bound_ctrl:1
	v_div_scale_f32 v87, s[6:7], v81, v81, 1.0
	s_nop 0
	v_add_f32_dpp v52, v52, v52 row_mirror row_mask:0xf bank_mask:0xf bound_ctrl:1
	v_div_scale_f32 v89, s[8:9], v80, v80, 1.0
	v_rcp_f32_e32 v91, v63
	v_mov_b32_dpp v84, v52 row_bcast:15 row_mask:0xa bank_mask:0xf
	v_rcp_f32_e32 v92, v83
	v_rcp_f32_e32 v93, v87
	v_rcp_f32_e32 v94, v89
	v_add_f32_e32 v52, v52, v84
	v_fma_f32 v84, -v63, v91, 1.0
	v_div_scale_f32 v82, vcc, 1.0, v79, 1.0
	v_mov_b32_dpp v85, v52 row_bcast:31 row_mask:0xc bank_mask:0xf
	v_add_f32_e32 v52, v52, v85
	v_fma_f32 v85, -v83, v92, 1.0
	v_readlane_b32 s10, v52, 63
	v_fma_f32 v52, -v87, v93, 1.0
	v_fma_f32 v95, -v89, v94, 1.0
	v_fmac_f32_e32 v91, v84, v91
	v_fma_f32 v84, s10, v9, v8
; DEVINL float bflo(unsigned u) { return __uint_as_float(u << 16); }
; DEVINL float bfhi(unsigned u) { return __uint_as_float(u & 0xffff0000u); }
; DEVINL float sigm(float x) { return 1.f / (1.f + __expf(-x)); }
; DEVINL void phase4(const Params& p) {
;     ...
;     float ss = o.x * o.x + o.y * o.y + o.z * o.z + o.w * o.w;
;     ss = allred64(ss);
;     const float rstd = rsqrtf(ss * (1.f / 256.f) + 1e-5f);
;     float4 ng = *(const float4*)(p.gla_norm_g + c);
;     uint2 gg = *(const uint2*)(cols + t * NCP + C_G + c);
;     float g0 = bflo(gg.x), g1 = bfhi(gg.x), g2 = bflo(gg.y), g3 = bfhi(gg.y);
;     float y0 = o.x * rstd * ng.x * (g0 * sigm(g0));
;     float y1 = o.y * rstd * ng.y * (g1 * sigm(g1));
;     float y2 = o.z * rstd * ng.z * (g2 * sigm(g2));
;     float y3 = o.w * rstd * ng.w * (g3 * sigm(g3));
;     *(uint2*)((u16*)(ws + O_YGLA) + t * 1024 + c) = make_uint2(pk2(y0, y1), pk2(y2, y3));
;   }
	v_div_scale_f32 v86, s[0:1], 1.0, v78, 1.0
	v_fmac_f32_e32 v92, v85, v92
	v_fmac_f32_e32 v93, v52, v93
	v_fmac_f32_e32 v94, v95, v94
	v_mul_f32_e32 v52, v82, v91
	v_mul_f32_e32 v95, 0x4b800000, v84
	v_cmp_gt_f32_e64 s[10:11], s23, v84
	v_div_scale_f32 v88, s[6:7], 1.0, v81, 1.0
	v_mul_f32_e32 v85, v86, v92
	v_fma_f32 v98, -v63, v52, v82
	v_cndmask_b32_e64 v84, v84, v95, s[10:11]
	v_div_scale_f32 v90, s[8:9], 1.0, v80, 1.0
	v_mul_f32_e32 v96, v88, v93
	v_fma_f32 v99, -v83, v85, v86
	v_fmac_f32_e32 v52, v98, v91
	v_rsq_f32_e32 v84, v84
	v_mul_f32_e32 v97, v90, v94
	v_fma_f32 v95, -v87, v96, v88
	v_fmac_f32_e32 v85, v99, v92
	v_fma_f32 v63, -v63, v52, v82
	v_fma_f32 v100, -v89, v97, v90
	v_fmac_f32_e32 v96, v95, v93
	v_fma_f32 v82, -v83, v85, v86
	v_div_fmas_f32 v52, v63, v91, v52
	s_mov_b64 vcc, s[0:1]
	v_fmac_f32_e32 v97, v100, v94
	v_fma_f32 v83, -v87, v96, v88
	v_div_fixup_f32 v79, v52, v79, 1.0
	v_div_fmas_f32 v52, v82, v92, v85
	s_mov_b64 vcc, s[6:7]
	v_fma_f32 v86, -v89, v97, v90
	v_div_fixup_f32 v78, v52, v78, 1.0
	v_mul_f32_e32 v52, 0x45800000, v84
	v_div_fmas_f32 v63, v83, v93, v96
	s_mov_b64 vcc, s[8:9]
	v_pk_mul_f32 v[76:77], v[78:79], v[76:77]
	v_cndmask_b32_e64 v52, v84, v52, s[10:11]
	v_div_fixup_f32 v79, v63, v81, 1.0
	v_div_fmas_f32 v63, v86, v94, v97
	v_pk_mul_f32 v[74:75], v[74:75], v[52:53] op_sel_hi:[1,0]
	v_pk_mul_f32 v[72:73], v[72:73], v[52:53] op_sel_hi:[1,0]
	v_div_fixup_f32 v78, v63, v80, 1.0
	v_pk_mul_f32 v[64:65], v[64:65], v[74:75]
	v_pk_mul_f32 v[66:67], v[66:67], v[72:73]
	v_pk_mul_f32 v[68:69], v[78:79], v[68:69]
	v_pk_mul_f32 v[64:65], v[64:65], v[76:77]
	v_pk_mul_f32 v[66:67], v[66:67], v[68:69]
	v_cvt_pk_bf16_f32 v64, v64, v65
	v_cvt_pk_bf16_f32 v65, v66, v67
	global_store_dwordx2 v[70:71], v[64:65], off
	s_waitcnt vmcnt(8)
	v_lshlrev_b32_e32 v128, 16, v124
	s_waitcnt vmcnt(7)
	v_lshlrev_b32_e32 v130, 16, v126
	v_and_b32_e32 v129, 0xffff0000, v124
	v_and_b32_e32 v131, 0xffff0000, v126
	v_lshlrev_b32_e32 v124, 16, v125
	v_lshlrev_b32_e32 v126, 16, v127
	v_and_b32_e32 v125, 0xffff0000, v125
	v_and_b32_e32 v127, 0xffff0000, v127
	v_pk_add_f32 v[124:125], v[124:125], v[126:127]
	v_pk_add_f32 v[126:127], v[128:129], v[130:131]
	s_waitcnt vmcnt(6)
	v_lshlrev_b32_e32 v128, 16, v120
	v_and_b32_e32 v129, 0xffff0000, v120
	v_pk_mul_f32 v[132:133], v[126:127], v[126:127]
	v_lshlrev_b32_e32 v120, 16, v121
	v_and_b32_e32 v121, 0xffff0000, v121
	v_pk_mul_f32 v[130:131], v[124:125], v[124:125]
	v_mul_f32_e32 v104, 0xbfb8aa3b, v128
	v_mul_f32_e32 v115, 0xbfb8aa3b, v129
	v_add_f32_e32 v134, v132, v133
	v_mul_f32_e32 v135, 0xbfb8aa3b, v120
	v_mul_f32_e32 v138, 0xbfb8aa3b, v121
	v_exp_f32_e32 v132, v104
	v_exp_f32_e32 v133, v115
	v_add_f32_e32 v104, v134, v130
	v_exp_f32_e32 v134, v135
	v_exp_f32_e32 v135, v138
	v_add_f32_e32 v104, v131, v104
	v_pk_add_f32 v[130:131], v[132:133], 1.0 op_sel_hi:[1,0]
	v_pk_add_f32 v[132:133], v[134:135], 1.0 op_sel_hi:[1,0]
	v_add_f32_dpp v104, v104, v104 quad_perm:[1,0,3,2] row_mask:0xf bank_mask:0xf bound_ctrl:1
	v_div_scale_f32 v115, s[0:1], v131, v131, 1.0
	s_nop 0
	v_add_f32_dpp v104, v104, v104 quad_perm:[2,3,0,1] row_mask:0xf bank_mask:0xf bound_ctrl:1
	v_div_scale_f32 v135, s[0:1], v130, v130, 1.0
	s_nop 0
	v_add_f32_dpp v104, v104, v104 row_half_mirror row_mask:0xf bank_mask:0xf bound_ctrl:1
	v_div_scale_f32 v139, s[6:7], v133, v133, 1.0
	s_nop 0
	v_add_f32_dpp v104, v104, v104 row_mirror row_mask:0xf bank_mask:0xf bound_ctrl:1
	v_div_scale_f32 v141, s[8:9], v132, v132, 1.0
	v_rcp_f32_e32 v143, v115
	v_mov_b32_dpp v136, v104 row_bcast:15 row_mask:0xa bank_mask:0xf
	v_rcp_f32_e32 v144, v135
	v_rcp_f32_e32 v145, v139
	v_rcp_f32_e32 v146, v141
	v_add_f32_e32 v104, v104, v136
	v_fma_f32 v136, -v115, v143, 1.0
	v_div_scale_f32 v134, vcc, 1.0, v131, 1.0
	v_mov_b32_dpp v137, v104 row_bcast:31 row_mask:0xc bank_mask:0xf
	v_add_f32_e32 v104, v104, v137
	v_fma_f32 v137, -v135, v144, 1.0
	v_readlane_b32 s10, v104, 63
	v_fma_f32 v104, -v139, v145, 1.0
	v_fma_f32 v147, -v141, v146, 1.0
	v_fmac_f32_e32 v143, v136, v143
	v_fma_f32 v136, s10, v9, v8
	v_div_scale_f32 v138, s[0:1], 1.0, v130, 1.0
	v_fmac_f32_e32 v144, v137, v144
	v_fmac_f32_e32 v145, v104, v145
	v_fmac_f32_e32 v146, v147, v146
	v_mul_f32_e32 v104, v134, v143
	v_mul_f32_e32 v147, 0x4b800000, v136
	v_cmp_gt_f32_e64 s[10:11], s23, v136
	v_div_scale_f32 v140, s[6:7], 1.0, v133, 1.0
	v_mul_f32_e32 v137, v138, v144
	v_fma_f32 v150, -v115, v104, v134
	v_cndmask_b32_e64 v136, v136, v147, s[10:11]
	v_div_scale_f32 v142, s[8:9], 1.0, v132, 1.0
	v_mul_f32_e32 v148, v140, v145
	v_fma_f32 v151, -v135, v137, v138
	v_fmac_f32_e32 v104, v150, v143
	v_rsq_f32_e32 v136, v136
	v_mul_f32_e32 v149, v142, v146
	v_fma_f32 v147, -v139, v148, v140
	v_fmac_f32_e32 v137, v151, v144
	v_fma_f32 v115, -v115, v104, v134
	v_fma_f32 v152, -v141, v149, v142
	v_fmac_f32_e32 v148, v147, v145
	v_fma_f32 v134, -v135, v137, v138
	v_div_fmas_f32 v104, v115, v143, v104
	s_mov_b64 vcc, s[0:1]
	v_fmac_f32_e32 v149, v152, v146
	v_fma_f32 v135, -v139, v148, v140
	v_div_fixup_f32 v131, v104, v131, 1.0
	v_div_fmas_f32 v104, v134, v144, v137
	s_mov_b64 vcc, s[6:7]
	v_fma_f32 v138, -v141, v149, v142
	v_div_fixup_f32 v130, v104, v130, 1.0
	v_mul_f32_e32 v104, 0x45800000, v136
	v_div_fmas_f32 v115, v135, v145, v148
	s_mov_b64 vcc, s[8:9]
	v_pk_mul_f32 v[128:129], v[130:131], v[128:129]
	v_cndmask_b32_e64 v104, v136, v104, s[10:11]
	v_div_fixup_f32 v131, v115, v133, 1.0
	v_div_fmas_f32 v115, v138, v146, v149
	v_pk_mul_f32 v[126:127], v[126:127], v[104:105] op_sel_hi:[1,0]
	v_pk_mul_f32 v[124:125], v[124:125], v[104:105] op_sel_hi:[1,0]
	v_div_fixup_f32 v130, v115, v132, 1.0
	v_pk_mul_f32 v[116:117], v[116:117], v[126:127]
	v_pk_mul_f32 v[118:119], v[118:119], v[124:125]
	v_pk_mul_f32 v[120:121], v[130:131], v[120:121]
	v_pk_mul_f32 v[116:117], v[116:117], v[128:129]
	v_pk_mul_f32 v[118:119], v[118:119], v[120:121]
	v_cvt_pk_bf16_f32 v116, v116, v117
	v_cvt_pk_bf16_f32 v117, v118, v119
	global_store_dwordx2 v[122:123], v[116:117], off
	s_waitcnt vmcnt(5)
; DEVINL float bflo(unsigned u) { return __uint_as_float(u << 16); }
; DEVINL float bfhi(unsigned u) { return __uint_as_float(u & 0xffff0000u); }
; DEVINL float sigm(float x) { return 1.f / (1.f + __expf(-x)); }
; DEVINL void phase4(const Params& p) {
;     ...
;     float ss = o.x * o.x + o.y * o.y + o.z * o.z + o.w * o.w;
;     ss = allred64(ss);
;     const float rstd = rsqrtf(ss * (1.f / 256.f) + 1e-5f);
;     float4 ng = *(const float4*)(p.gla_norm_g + c);
;     uint2 gg = *(const uint2*)(cols + t * NCP + C_G + c);
;     float g0 = bflo(gg.x), g1 = bfhi(gg.x), g2 = bflo(gg.y), g3 = bfhi(gg.y);
;     float y0 = o.x * rstd * ng.x * (g0 * sigm(g0));
;     float y1 = o.y * rstd * ng.y * (g1 * sigm(g1));
;     float y2 = o.z * rstd * ng.z * (g2 * sigm(g2));
;     float y3 = o.w * rstd * ng.w * (g3 * sigm(g3));
;     *(uint2*)((u16*)(ws + O_YGLA) + t * 1024 + c) = make_uint2(pk2(y0, y1), pk2(y2, y3));
;   }
;   for (int u = gw; u < T_ * 4; u += nw) {
;     const long t = u >> 2; const int hq = u & 3;
;     const int c = (hq * 4 + (lane >> 4)) * 64 + (lane & 15) * 4;
	v_lshlrev_b32_e32 v224, 16, v220
	s_waitcnt vmcnt(4)
	v_lshlrev_b32_e32 v226, 16, v222
	v_and_b32_e32 v225, 0xffff0000, v220
	v_and_b32_e32 v227, 0xffff0000, v222
	v_lshlrev_b32_e32 v220, 16, v221
	v_lshlrev_b32_e32 v222, 16, v223
	v_and_b32_e32 v221, 0xffff0000, v221
	v_and_b32_e32 v223, 0xffff0000, v223
	v_pk_add_f32 v[220:221], v[220:221], v[222:223]
	v_pk_add_f32 v[222:223], v[224:225], v[226:227]
	s_waitcnt vmcnt(3)
	v_lshlrev_b32_e32 v224, 16, v216
	v_and_b32_e32 v225, 0xffff0000, v216
	v_pk_mul_f32 v[228:229], v[222:223], v[222:223]
	v_lshlrev_b32_e32 v216, 16, v217
	v_and_b32_e32 v217, 0xffff0000, v217
	v_pk_mul_f32 v[226:227], v[220:221], v[220:221]
	v_mul_f32_e32 v200, 0xbfb8aa3b, v224
	v_mul_f32_e32 v211, 0xbfb8aa3b, v225
	v_add_f32_e32 v230, v228, v229
	v_mul_f32_e32 v231, 0xbfb8aa3b, v216
	v_mul_f32_e32 v234, 0xbfb8aa3b, v217
	v_exp_f32_e32 v228, v200
	v_exp_f32_e32 v229, v211
	v_add_f32_e32 v200, v230, v226
	v_exp_f32_e32 v230, v231
	v_exp_f32_e32 v231, v234
	v_add_f32_e32 v200, v227, v200
	v_pk_add_f32 v[226:227], v[228:229], 1.0 op_sel_hi:[1,0]
	v_pk_add_f32 v[228:229], v[230:231], 1.0 op_sel_hi:[1,0]
	v_add_f32_dpp v200, v200, v200 quad_perm:[1,0,3,2] row_mask:0xf bank_mask:0xf bound_ctrl:1
	v_div_scale_f32 v211, s[0:1], v227, v227, 1.0
	s_nop 0
	v_add_f32_dpp v200, v200, v200 quad_perm:[2,3,0,1] row_mask:0xf bank_mask:0xf bound_ctrl:1
	v_div_scale_f32 v231, s[0:1], v226, v226, 1.0
	s_nop 0
	v_add_f32_dpp v200, v200, v200 row_half_mirror row_mask:0xf bank_mask:0xf bound_ctrl:1
	v_div_scale_f32 v235, s[6:7], v229, v229, 1.0
	s_nop 0
	v_add_f32_dpp v200, v200, v200 row_mirror row_mask:0xf bank_mask:0xf bound_ctrl:1
	v_div_scale_f32 v237, s[8:9], v228, v228, 1.0
	v_rcp_f32_e32 v239, v211
	v_mov_b32_dpp v232, v200 row_bcast:15 row_mask:0xa bank_mask:0xf
	v_rcp_f32_e32 v240, v231
	v_rcp_f32_e32 v241, v235
	v_rcp_f32_e32 v242, v237
	v_add_f32_e32 v200, v200, v232
	v_fma_f32 v232, -v211, v239, 1.0
	v_div_scale_f32 v230, vcc, 1.0, v227, 1.0
	v_mov_b32_dpp v233, v200 row_bcast:31 row_mask:0xc bank_mask:0xf
	v_add_f32_e32 v200, v200, v233
	v_fma_f32 v233, -v231, v240, 1.0
	v_readlane_b32 s10, v200, 63
	v_fma_f32 v200, -v235, v241, 1.0
	v_fma_f32 v243, -v237, v242, 1.0
	v_fmac_f32_e32 v239, v232, v239
	v_fma_f32 v232, s10, v9, v8
	v_div_scale_f32 v234, s[0:1], 1.0, v226, 1.0
	v_fmac_f32_e32 v240, v233, v240
	v_fmac_f32_e32 v241, v200, v241
	v_fmac_f32_e32 v242, v243, v242
	v_mul_f32_e32 v200, v230, v239
	v_mul_f32_e32 v243, 0x4b800000, v232
	v_cmp_gt_f32_e64 s[10:11], s23, v232
	v_div_scale_f32 v236, s[6:7], 1.0, v229, 1.0
	v_mul_f32_e32 v233, v234, v240
	v_fma_f32 v246, -v211, v200, v230
	v_cndmask_b32_e64 v232, v232, v243, s[10:11]
	v_div_scale_f32 v238, s[8:9], 1.0, v228, 1.0
	v_mul_f32_e32 v244, v236, v241
	v_fma_f32 v247, -v231, v233, v234
	v_fmac_f32_e32 v200, v246, v239
	v_rsq_f32_e32 v232, v232
	v_mul_f32_e32 v245, v238, v242
	v_fma_f32 v243, -v235, v244, v236
	v_fmac_f32_e32 v233, v247, v240
	v_fma_f32 v211, -v211, v200, v230
	v_fma_f32 v248, -v237, v245, v238
	v_fmac_f32_e32 v244, v243, v241
	v_fma_f32 v230, -v231, v233, v234
	v_div_fmas_f32 v200, v211, v239, v200
	s_mov_b64 vcc, s[0:1]
	v_fmac_f32_e32 v245, v248, v242
	v_fma_f32 v231, -v235, v244, v236
	v_div_fixup_f32 v227, v200, v227, 1.0
	v_div_fmas_f32 v200, v230, v240, v233
	s_mov_b64 vcc, s[6:7]
	v_fma_f32 v234, -v237, v245, v238
	v_div_fixup_f32 v226, v200, v226, 1.0
	v_mul_f32_e32 v200, 0x45800000, v232
	v_div_fmas_f32 v211, v231, v241, v244
	s_mov_b64 vcc, s[8:9]
	v_pk_mul_f32 v[224:225], v[226:227], v[224:225]
	v_cndmask_b32_e64 v200, v232, v200, s[10:11]
	v_div_fixup_f32 v227, v211, v229, 1.0
	v_div_fmas_f32 v211, v234, v242, v245
	v_pk_mul_f32 v[222:223], v[222:223], v[200:201] op_sel_hi:[1,0]
	v_pk_mul_f32 v[220:221], v[220:221], v[200:201] op_sel_hi:[1,0]
	v_div_fixup_f32 v226, v211, v228, 1.0
	v_pk_mul_f32 v[212:213], v[212:213], v[222:223]
	v_pk_mul_f32 v[214:215], v[214:215], v[220:221]
	v_pk_mul_f32 v[216:217], v[226:227], v[216:217]
	v_pk_mul_f32 v[212:213], v[212:213], v[224:225]
	v_pk_mul_f32 v[214:215], v[214:215], v[216:217]
	v_cvt_pk_bf16_f32 v212, v212, v213
	v_cvt_pk_bf16_f32 v213, v214, v215
	global_store_dwordx2 v[218:219], v[212:213], off
	s_andn2_b64 exec, exec, s[18:19]
	s_cbranch_execnz .LBB0_552
	s_or_b64 exec, exec, s[18:19]
	s_add_u32 s0, s92, 0x1f700000
	s_addc_u32 s1, s93, 0
	s_add_u32 s6, s92, 0x1d500000
	s_addc_u32 s7, s93, 0
	s_add_u32 s8, s92, 0x1c500000
	v_lshlrev_b32_e32 v0, 2, v4
	s_addc_u32 s9, s93, 0
	v_and_b32_e32 v4, 60, v0
	s_add_u32 s10, s92, 0x10400000
	v_lshlrev_b32_e32 v0, 2, v3
	v_lshrrev_b32_e32 v5, 4, v5
	s_addc_u32 s11, s93, 0
	v_lshl_add_u32 v3, s2, 5, v0
	s_lshl_b32 s3, s94, 5
	s_mov_b64 s[14:15], 0
	v_mov_b32_e32 v1, 0
	v_mov_b32_e32 v6, 0x3a27c5ac
	s_mov_b32 s16, 0x800000
	s_movk_i32 s17, 0x7fff
	v_mov_b32_e32 v53, v1
	v_mov_b32_e32 v105, v1
	v_mov_b32_e32 v201, v1
; DEVINL float bflo(unsigned u) { return __uint_as_float(u << 16); }
; DEVINL float bfhi(unsigned u) { return __uint_as_float(u & 0xffff0000u); }
; DEVINL void phase4(const Params& p) {
;     ...
;   for (int u = gw; u < T_ * 4; u += nw) {
;     const long t = u >> 2; const int hq = u & 3;
;     const int c = (hq * 4 + (lane >> 4)) * 64 + (lane & 15) * 4;
;     float4 y;
;     {
;       const uint2 y1 = *(const uint2*)((const u16*)(ws + O_YSUM) + t * 1024 + c);
;       const uint2 y2 = *(const uint2*)((const u16*)(ws + O_YB) + t * 1024 + c);
;       y.x = bflo(y1.x) + bflo(y2.x); y.y = bfhi(y1.x) + bfhi(y2.x);
;       y.z = bflo(y1.y) + bflo(y2.y); y.w = bfhi(y1.y) + bfhi(y2.y);
;     }
.LBB0_554:
	v_ashrrev_i32_e32 v8, 2, v2
	v_and_or_b32 v0, v3, 12, v5
	v_ashrrev_i32_e32 v9, 31, v8
	v_lshl_or_b32 v7, v0, 6, v4
	v_lshlrev_b64 v[16:17], 11, v[8:9]
	v_lshlrev_b32_e32 v0, 1, v7
	v_lshl_add_u64 v[18:19], s[34:35], 0, v[16:17]
	v_lshl_add_u64 v[20:21], s[0:1], 0, v[16:17]
	v_lshl_add_u64 v[22:23], s[6:7], 0, v[16:17]
	v_lshl_add_u64 v[24:25], s[8:9], 0, v[16:17]
	v_lshlrev_b32_e32 v7, 2, v7
	v_lshl_add_u64 v[18:19], v[18:19], 0, v[0:1]
	v_lshl_add_u64 v[20:21], v[20:21], 0, v[0:1]
	v_lshl_add_u64 v[22:23], v[22:23], 0, v[0:1]
	v_lshl_add_u64 v[24:25], v[24:25], 0, v[0:1]
	global_load_dwordx4 v[8:11], v7, s[64:65]
	global_load_dwordx4 v[12:15], v7, s[66:67]
	s_nop 0
	global_load_dwordx2 v[18:19], v[18:19], off
	s_nop 0
	global_load_dwordx2 v[20:21], v[20:21], off
	s_nop 0
	global_load_dwordx2 v[22:23], v[22:23], off
	s_nop 0
	global_load_dwordx2 v[24:25], v[24:25], off
	v_lshl_add_u64 v[16:17], s[10:11], 0, v[16:17]
	v_lshl_add_u64 v[16:17], v[16:17], 0, v[0:1]
	v_add_u32_e32 v2, s60, v2
	v_cmp_lt_i32_e32 vcc, s17, v2
	s_or_b64 s[14:15], vcc, s[14:15]
	v_add_u32_e32 v3, s3, v3
	v_ashrrev_i32_e32 v60, 2, v2
	v_and_or_b32 v52, v3, 12, v5
	v_ashrrev_i32_e32 v61, 31, v60
	v_lshl_or_b32 v59, v52, 6, v4
	v_lshlrev_b64 v[68:69], 11, v[60:61]
	v_lshlrev_b32_e32 v52, 1, v59
	v_lshl_add_u64 v[70:71], s[34:35], 0, v[68:69]
	v_lshl_add_u64 v[72:73], s[0:1], 0, v[68:69]
	v_lshl_add_u64 v[74:75], s[6:7], 0, v[68:69]
	v_lshl_add_u64 v[76:77], s[8:9], 0, v[68:69]
	v_lshlrev_b32_e32 v59, 2, v59
	v_lshl_add_u64 v[70:71], v[70:71], 0, v[52:53]
	v_lshl_add_u64 v[72:73], v[72:73], 0, v[52:53]
	v_lshl_add_u64 v[74:75], v[74:75], 0, v[52:53]
	v_lshl_add_u64 v[76:77], v[76:77], 0, v[52:53]
	global_load_dwordx4 v[60:63], v59, s[64:65]
	global_load_dwordx4 v[64:67], v59, s[66:67]
	s_nop 0
	global_load_dwordx2 v[70:71], v[70:71], off
	s_nop 0
	global_load_dwordx2 v[72:73], v[72:73], off
	s_nop 0
	global_load_dwordx2 v[74:75], v[74:75], off
	s_nop 0
	global_load_dwordx2 v[76:77], v[76:77], off
	v_lshl_add_u64 v[68:69], s[10:11], 0, v[68:69]
	v_lshl_add_u64 v[68:69], v[68:69], 0, v[52:53]
	v_add_u32_e32 v2, s60, v2
	v_cmp_lt_i32_e32 vcc, s17, v2
	s_or_b64 s[14:15], vcc, s[14:15]
	v_add_u32_e32 v3, s3, v3
	v_ashrrev_i32_e32 v112, 2, v2
	v_and_or_b32 v104, v3, 12, v5
	v_ashrrev_i32_e32 v113, 31, v112
	v_lshl_or_b32 v111, v104, 6, v4
	v_lshlrev_b64 v[120:121], 11, v[112:113]
	v_lshlrev_b32_e32 v104, 1, v111
	v_lshl_add_u64 v[122:123], s[34:35], 0, v[120:121]
	v_lshl_add_u64 v[124:125], s[0:1], 0, v[120:121]
	v_lshl_add_u64 v[126:127], s[6:7], 0, v[120:121]
	v_lshl_add_u64 v[128:129], s[8:9], 0, v[120:121]
	v_lshlrev_b32_e32 v111, 2, v111
	v_lshl_add_u64 v[122:123], v[122:123], 0, v[104:105]
	v_lshl_add_u64 v[124:125], v[124:125], 0, v[104:105]
	v_lshl_add_u64 v[126:127], v[126:127], 0, v[104:105]
	v_lshl_add_u64 v[128:129], v[128:129], 0, v[104:105]
	global_load_dwordx4 v[112:115], v111, s[64:65]
	global_load_dwordx4 v[116:119], v111, s[66:67]
	s_nop 0
	global_load_dwordx2 v[122:123], v[122:123], off
	s_nop 0
	global_load_dwordx2 v[124:125], v[124:125], off
	s_nop 0
	global_load_dwordx2 v[126:127], v[126:127], off
	s_nop 0
	global_load_dwordx2 v[128:129], v[128:129], off
	v_lshl_add_u64 v[120:121], s[10:11], 0, v[120:121]
	v_lshl_add_u64 v[120:121], v[120:121], 0, v[104:105]
	v_add_u32_e32 v2, s60, v2
	v_cmp_lt_i32_e32 vcc, s17, v2
	s_or_b64 s[14:15], vcc, s[14:15]
	v_add_u32_e32 v3, s3, v3
	v_ashrrev_i32_e32 v208, 2, v2
	v_and_or_b32 v200, v3, 12, v5
	v_ashrrev_i32_e32 v209, 31, v208
	v_lshl_or_b32 v207, v200, 6, v4
	v_lshlrev_b64 v[216:217], 11, v[208:209]
	v_lshlrev_b32_e32 v200, 1, v207
	v_lshl_add_u64 v[218:219], s[34:35], 0, v[216:217]
	v_lshl_add_u64 v[220:221], s[0:1], 0, v[216:217]
	v_lshl_add_u64 v[222:223], s[6:7], 0, v[216:217]
	v_lshl_add_u64 v[224:225], s[8:9], 0, v[216:217]
	v_lshlrev_b32_e32 v207, 2, v207
	v_lshl_add_u64 v[218:219], v[218:219], 0, v[200:201]
	v_lshl_add_u64 v[220:221], v[220:221], 0, v[200:201]
	v_lshl_add_u64 v[222:223], v[222:223], 0, v[200:201]
	v_lshl_add_u64 v[224:225], v[224:225], 0, v[200:201]
	global_load_dwordx4 v[208:211], v207, s[64:65]
	global_load_dwordx4 v[212:215], v207, s[66:67]
	s_nop 0
	global_load_dwordx2 v[218:219], v[218:219], off
	s_nop 0
	global_load_dwordx2 v[220:221], v[220:221], off
	s_nop 0
	global_load_dwordx2 v[222:223], v[222:223], off
	s_nop 0
	global_load_dwordx2 v[224:225], v[224:225], off
	v_lshl_add_u64 v[216:217], s[10:11], 0, v[216:217]
	v_lshl_add_u64 v[216:217], v[216:217], 0, v[200:201]
	v_add_u32_e32 v2, s60, v2
	v_cmp_lt_i32_e32 vcc, s17, v2
	s_or_b64 s[14:15], vcc, s[14:15]
	v_add_u32_e32 v3, s3, v3
	s_waitcnt vmcnt(21)
	v_lshlrev_b32_e32 v26, 16, v18
	s_waitcnt vmcnt(20)
	v_lshlrev_b32_e32 v28, 16, v20
	v_and_b32_e32 v27, 0xffff0000, v18
	v_and_b32_e32 v29, 0xffff0000, v20
	v_lshlrev_b32_e32 v18, 16, v19
	v_lshlrev_b32_e32 v20, 16, v21
	v_and_b32_e32 v19, 0xffff0000, v19
	v_and_b32_e32 v21, 0xffff0000, v21
	v_pk_add_f32 v[18:19], v[18:19], v[20:21]
	v_pk_add_f32 v[20:21], v[26:27], v[28:29]
	s_waitcnt vmcnt(19)
	v_lshlrev_b32_e32 v30, 16, v22
	v_add_f32_e32 v0, v20, v21
	v_add_f32_e32 v0, v0, v18
	v_add_f32_e32 v0, v19, v0
	v_and_b32_e32 v31, 0xffff0000, v22
	v_lshlrev_b32_e32 v22, 16, v23
	v_add_f32_dpp v0, v0, v0 quad_perm:[1,0,3,2] row_mask:0xf bank_mask:0xf bound_ctrl:1
	v_and_b32_e32 v23, 0xffff0000, v23
	s_waitcnt vmcnt(18)
; DEVINL float bflo(unsigned u) { return __uint_as_float(u << 16); }
; DEVINL float bfhi(unsigned u) { return __uint_as_float(u & 0xffff0000u); }
; DEVINL void phase4(const Params& p) {
;     ...
;     float mu = allred16(y.x + y.y + y.z + y.w) * (1.f / 64.f);
;     float d0 = y.x - mu, d1 = y.y - mu, d2 = y.z - mu, d3 = y.w - mu;
;     float var = allred16(d0 * d0 + d1 * d1 + d2 * d2 + d3 * d3) * (1.f / 64.f);
;     const float rstd = rsqrtf(var + 64e-5f);
;     float4 lg = *(const float4*)(p.rw_ln_g + c);
;     float4 lb = *(const float4*)(p.rw_ln_b + c);
;     uint2 bo = *(const uint2*)((const u16*)(ws + O_BONUS) + t * 1024 + c);
;     uint2 gg = *(const uint2*)((const u16*)(ws + O_GRW) + t * 1024 + c);
;     float r0 = (d0 * rstd * lg.x + lb.x + bflo(bo.x)) * bflo(gg.x);
;     float r1 = (d1 * rstd * lg.y + lb.y + bfhi(bo.x)) * bfhi(gg.x);
;     float r2 = (d2 * rstd * lg.z + lb.z + bflo(bo.y)) * bflo(gg.y);
;     float r3 = (d3 * rstd * lg.w + lb.w + bfhi(bo.y)) * bfhi(gg.y);
;     *(uint2*)((u16*)(ws + O_YRW) + t * 1024 + c) = make_uint2(pk2(r0, r1), pk2(r2, r3));
	v_lshlrev_b32_e32 v32, 16, v24
	v_add_f32_dpp v0, v0, v0 quad_perm:[2,3,0,1] row_mask:0xf bank_mask:0xf bound_ctrl:1
	v_and_b32_e32 v33, 0xffff0000, v24
	v_lshlrev_b32_e32 v24, 16, v25
	v_add_f32_dpp v0, v0, v0 row_half_mirror row_mask:0xf bank_mask:0xf bound_ctrl:1
	v_and_b32_e32 v25, 0xffff0000, v25
	s_nop 0
	v_add_f32_dpp v0, v0, v0 row_mirror row_mask:0xf bank_mask:0xf bound_ctrl:1
	v_mul_f32_e32 v0, 0x3c800000, v0
	v_pk_add_f32 v[20:21], v[20:21], v[0:1] op_sel_hi:[1,0] neg_lo:[0,1] neg_hi:[0,1]
	v_pk_add_f32 v[18:19], v[18:19], v[0:1] op_sel_hi:[1,0] neg_lo:[0,1] neg_hi:[0,1]
	v_pk_mul_f32 v[26:27], v[20:21], v[20:21]
	v_pk_mul_f32 v[28:29], v[18:19], v[18:19]
	v_add_f32_e32 v0, v26, v27
	v_add_f32_e32 v0, v28, v0
	v_add_f32_e32 v0, v29, v0
	s_nop 1
	v_add_f32_dpp v0, v0, v0 quad_perm:[1,0,3,2] row_mask:0xf bank_mask:0xf bound_ctrl:1
	s_nop 1
	v_add_f32_dpp v0, v0, v0 quad_perm:[2,3,0,1] row_mask:0xf bank_mask:0xf bound_ctrl:1
	s_nop 1
	v_add_f32_dpp v0, v0, v0 row_half_mirror row_mask:0xf bank_mask:0xf bound_ctrl:1
	s_nop 1
	v_add_f32_dpp v0, v0, v0 row_mirror row_mask:0xf bank_mask:0xf bound_ctrl:1
	v_fmamk_f32 v0, v0, 0x3c800000, v6
	v_mul_f32_e32 v7, 0x4b800000, v0
	v_cmp_gt_f32_e32 vcc, s16, v0
	s_nop 1
	v_cndmask_b32_e32 v0, v0, v7, vcc
	v_rsq_f32_e32 v0, v0
	s_nop 0
	v_mul_f32_e32 v7, 0x45800000, v0
	v_cndmask_b32_e32 v0, v0, v7, vcc
	v_pk_mul_f32 v[20:21], v[20:21], v[0:1] op_sel_hi:[1,0]
	v_pk_mul_f32 v[18:19], v[18:19], v[0:1] op_sel_hi:[1,0]
	v_pk_fma_f32 v[8:9], v[8:9], v[20:21], v[12:13]
	v_pk_fma_f32 v[10:11], v[10:11], v[18:19], v[14:15]
	v_pk_add_f32 v[8:9], v[8:9], v[30:31]
	v_pk_add_f32 v[10:11], v[10:11], v[22:23]
	v_pk_mul_f32 v[8:9], v[8:9], v[32:33]
	v_pk_mul_f32 v[10:11], v[10:11], v[24:25]
	v_cvt_pk_bf16_f32 v8, v8, v9
	v_cvt_pk_bf16_f32 v9, v10, v11
	global_store_dwordx2 v[16:17], v[8:9], off
	s_waitcnt vmcnt(16)
	v_lshlrev_b32_e32 v78, 16, v70
	s_waitcnt vmcnt(15)
	v_lshlrev_b32_e32 v80, 16, v72
	v_and_b32_e32 v79, 0xffff0000, v70
	v_and_b32_e32 v81, 0xffff0000, v72
	v_lshlrev_b32_e32 v70, 16, v71
	v_lshlrev_b32_e32 v72, 16, v73
	v_and_b32_e32 v71, 0xffff0000, v71
	v_and_b32_e32 v73, 0xffff0000, v73
	v_pk_add_f32 v[70:71], v[70:71], v[72:73]
	v_pk_add_f32 v[72:73], v[78:79], v[80:81]
	s_waitcnt vmcnt(14)
	v_lshlrev_b32_e32 v82, 16, v74
	v_add_f32_e32 v52, v72, v73
	v_add_f32_e32 v52, v52, v70
	v_add_f32_e32 v52, v71, v52
	v_and_b32_e32 v83, 0xffff0000, v74
	v_lshlrev_b32_e32 v74, 16, v75
	v_add_f32_dpp v52, v52, v52 quad_perm:[1,0,3,2] row_mask:0xf bank_mask:0xf bound_ctrl:1
	v_and_b32_e32 v75, 0xffff0000, v75
	s_waitcnt vmcnt(13)
	v_lshlrev_b32_e32 v84, 16, v76
	v_add_f32_dpp v52, v52, v52 quad_perm:[2,3,0,1] row_mask:0xf bank_mask:0xf bound_ctrl:1
	v_and_b32_e32 v85, 0xffff0000, v76
	v_lshlrev_b32_e32 v76, 16, v77
	v_add_f32_dpp v52, v52, v52 row_half_mirror row_mask:0xf bank_mask:0xf bound_ctrl:1
	v_and_b32_e32 v77, 0xffff0000, v77
	s_nop 0
	v_add_f32_dpp v52, v52, v52 row_mirror row_mask:0xf bank_mask:0xf bound_ctrl:1
	v_mul_f32_e32 v52, 0x3c800000, v52
	v_pk_add_f32 v[72:73], v[72:73], v[52:53] op_sel_hi:[1,0] neg_lo:[0,1] neg_hi:[0,1]
	v_pk_add_f32 v[70:71], v[70:71], v[52:53] op_sel_hi:[1,0] neg_lo:[0,1] neg_hi:[0,1]
	v_pk_mul_f32 v[78:79], v[72:73], v[72:73]
	v_pk_mul_f32 v[80:81], v[70:71], v[70:71]
	v_add_f32_e32 v52, v78, v79
	v_add_f32_e32 v52, v80, v52
	v_add_f32_e32 v52, v81, v52
	s_nop 1
	v_add_f32_dpp v52, v52, v52 quad_perm:[1,0,3,2] row_mask:0xf bank_mask:0xf bound_ctrl:1
	s_nop 1
	v_add_f32_dpp v52, v52, v52 quad_perm:[2,3,0,1] row_mask:0xf bank_mask:0xf bound_ctrl:1
	s_nop 1
	v_add_f32_dpp v52, v52, v52 row_half_mirror row_mask:0xf bank_mask:0xf bound_ctrl:1
	s_nop 1
	v_add_f32_dpp v52, v52, v52 row_mirror row_mask:0xf bank_mask:0xf bound_ctrl:1
	v_fmamk_f32 v52, v52, 0x3c800000, v6
	v_mul_f32_e32 v59, 0x4b800000, v52
	v_cmp_gt_f32_e32 vcc, s16, v52
	s_nop 1
	v_cndmask_b32_e32 v52, v52, v59, vcc
	v_rsq_f32_e32 v52, v52
	s_nop 0
	v_mul_f32_e32 v59, 0x45800000, v52
	v_cndmask_b32_e32 v52, v52, v59, vcc
	v_pk_mul_f32 v[72:73], v[72:73], v[52:53] op_sel_hi:[1,0]
	v_pk_mul_f32 v[70:71], v[70:71], v[52:53] op_sel_hi:[1,0]
	v_pk_fma_f32 v[60:61], v[60:61], v[72:73], v[64:65]
	v_pk_fma_f32 v[62:63], v[62:63], v[70:71], v[66:67]
	v_pk_add_f32 v[60:61], v[60:61], v[82:83]
	v_pk_add_f32 v[62:63], v[62:63], v[74:75]
	v_pk_mul_f32 v[60:61], v[60:61], v[84:85]
	v_pk_mul_f32 v[62:63], v[62:63], v[76:77]
	v_cvt_pk_bf16_f32 v60, v60, v61
	v_cvt_pk_bf16_f32 v61, v62, v63
	global_store_dwordx2 v[68:69], v[60:61], off
	s_waitcnt vmcnt(11)
	v_lshlrev_b32_e32 v130, 16, v122
	s_waitcnt vmcnt(10)
	v_lshlrev_b32_e32 v132, 16, v124
	v_and_b32_e32 v131, 0xffff0000, v122
	v_and_b32_e32 v133, 0xffff0000, v124
	v_lshlrev_b32_e32 v122, 16, v123
	v_lshlrev_b32_e32 v124, 16, v125
	v_and_b32_e32 v123, 0xffff0000, v123
	v_and_b32_e32 v125, 0xffff0000, v125
	v_pk_add_f32 v[122:123], v[122:123], v[124:125]
	v_pk_add_f32 v[124:125], v[130:131], v[132:133]
	s_waitcnt vmcnt(9)
	v_lshlrev_b32_e32 v134, 16, v126
	v_add_f32_e32 v104, v124, v125
	v_add_f32_e32 v104, v104, v122
	v_add_f32_e32 v104, v123, v104
	v_and_b32_e32 v135, 0xffff0000, v126
	v_lshlrev_b32_e32 v126, 16, v127
	v_add_f32_dpp v104, v104, v104 quad_perm:[1,0,3,2] row_mask:0xf bank_mask:0xf bound_ctrl:1
	v_and_b32_e32 v127, 0xffff0000, v127
	s_waitcnt vmcnt(8)
; DEVINL float bflo(unsigned u) { return __uint_as_float(u << 16); }
; DEVINL float bfhi(unsigned u) { return __uint_as_float(u & 0xffff0000u); }
; DEVINL void phase4(const Params& p) {
;     ...
;     float mu = allred16(y.x + y.y + y.z + y.w) * (1.f / 64.f);
;     float d0 = y.x - mu, d1 = y.y - mu, d2 = y.z - mu, d3 = y.w - mu;
;     float var = allred16(d0 * d0 + d1 * d1 + d2 * d2 + d3 * d3) * (1.f / 64.f);
;     const float rstd = rsqrtf(var + 64e-5f);
;     float4 lg = *(const float4*)(p.rw_ln_g + c);
;     float4 lb = *(const float4*)(p.rw_ln_b + c);
;     uint2 bo = *(const uint2*)((const u16*)(ws + O_BONUS) + t * 1024 + c);
;     uint2 gg = *(const uint2*)((const u16*)(ws + O_GRW) + t * 1024 + c);
;     float r0 = (d0 * rstd * lg.x + lb.x + bflo(bo.x)) * bflo(gg.x);
;     float r1 = (d1 * rstd * lg.y + lb.y + bfhi(bo.x)) * bfhi(gg.x);
;     float r2 = (d2 * rstd * lg.z + lb.z + bflo(bo.y)) * bflo(gg.y);
;     float r3 = (d3 * rstd * lg.w + lb.w + bfhi(bo.y)) * bfhi(gg.y);
;     *(uint2*)((u16*)(ws + O_YRW) + t * 1024 + c) = make_uint2(pk2(r0, r1), pk2(r2, r3));
	v_lshlrev_b32_e32 v136, 16, v128
	v_add_f32_dpp v104, v104, v104 quad_perm:[2,3,0,1] row_mask:0xf bank_mask:0xf bound_ctrl:1
	v_and_b32_e32 v137, 0xffff0000, v128
	v_lshlrev_b32_e32 v128, 16, v129
	v_add_f32_dpp v104, v104, v104 row_half_mirror row_mask:0xf bank_mask:0xf bound_ctrl:1
	v_and_b32_e32 v129, 0xffff0000, v129
	s_nop 0
	v_add_f32_dpp v104, v104, v104 row_mirror row_mask:0xf bank_mask:0xf bound_ctrl:1
	v_mul_f32_e32 v104, 0x3c800000, v104
	v_pk_add_f32 v[124:125], v[124:125], v[104:105] op_sel_hi:[1,0] neg_lo:[0,1] neg_hi:[0,1]
	v_pk_add_f32 v[122:123], v[122:123], v[104:105] op_sel_hi:[1,0] neg_lo:[0,1] neg_hi:[0,1]
	v_pk_mul_f32 v[130:131], v[124:125], v[124:125]
	v_pk_mul_f32 v[132:133], v[122:123], v[122:123]
	v_add_f32_e32 v104, v130, v131
	v_add_f32_e32 v104, v132, v104
	v_add_f32_e32 v104, v133, v104
	s_nop 1
	v_add_f32_dpp v104, v104, v104 quad_perm:[1,0,3,2] row_mask:0xf bank_mask:0xf bound_ctrl:1
	s_nop 1
	v_add_f32_dpp v104, v104, v104 quad_perm:[2,3,0,1] row_mask:0xf bank_mask:0xf bound_ctrl:1
	s_nop 1
	v_add_f32_dpp v104, v104, v104 row_half_mirror row_mask:0xf bank_mask:0xf bound_ctrl:1
	s_nop 1
	v_add_f32_dpp v104, v104, v104 row_mirror row_mask:0xf bank_mask:0xf bound_ctrl:1
	v_fmamk_f32 v104, v104, 0x3c800000, v6
	v_mul_f32_e32 v111, 0x4b800000, v104
	v_cmp_gt_f32_e32 vcc, s16, v104
	s_nop 1
	v_cndmask_b32_e32 v104, v104, v111, vcc
	v_rsq_f32_e32 v104, v104
	s_nop 0
	v_mul_f32_e32 v111, 0x45800000, v104
	v_cndmask_b32_e32 v104, v104, v111, vcc
	v_pk_mul_f32 v[124:125], v[124:125], v[104:105] op_sel_hi:[1,0]
	v_pk_mul_f32 v[122:123], v[122:123], v[104:105] op_sel_hi:[1,0]
	v_pk_fma_f32 v[112:113], v[112:113], v[124:125], v[116:117]
	v_pk_fma_f32 v[114:115], v[114:115], v[122:123], v[118:119]
	v_pk_add_f32 v[112:113], v[112:113], v[134:135]
	v_pk_add_f32 v[114:115], v[114:115], v[126:127]
	v_pk_mul_f32 v[112:113], v[112:113], v[136:137]
	v_pk_mul_f32 v[114:115], v[114:115], v[128:129]
	v_cvt_pk_bf16_f32 v112, v112, v113
	v_cvt_pk_bf16_f32 v113, v114, v115
	global_store_dwordx2 v[120:121], v[112:113], off
	s_waitcnt vmcnt(6)
	v_lshlrev_b32_e32 v226, 16, v218
	s_waitcnt vmcnt(5)
	v_lshlrev_b32_e32 v228, 16, v220
	v_and_b32_e32 v227, 0xffff0000, v218
	v_and_b32_e32 v229, 0xffff0000, v220
	v_lshlrev_b32_e32 v218, 16, v219
	v_lshlrev_b32_e32 v220, 16, v221
	v_and_b32_e32 v219, 0xffff0000, v219
	v_and_b32_e32 v221, 0xffff0000, v221
	v_pk_add_f32 v[218:219], v[218:219], v[220:221]
	v_pk_add_f32 v[220:221], v[226:227], v[228:229]
	s_waitcnt vmcnt(4)
	v_lshlrev_b32_e32 v230, 16, v222
	v_add_f32_e32 v200, v220, v221
	v_add_f32_e32 v200, v200, v218
	v_add_f32_e32 v200, v219, v200
	v_and_b32_e32 v231, 0xffff0000, v222
	v_lshlrev_b32_e32 v222, 16, v223
	v_add_f32_dpp v200, v200, v200 quad_perm:[1,0,3,2] row_mask:0xf bank_mask:0xf bound_ctrl:1
	v_and_b32_e32 v223, 0xffff0000, v223
	s_waitcnt vmcnt(3)
	v_lshlrev_b32_e32 v232, 16, v224
	v_add_f32_dpp v200, v200, v200 quad_perm:[2,3,0,1] row_mask:0xf bank_mask:0xf bound_ctrl:1
	v_and_b32_e32 v233, 0xffff0000, v224
	v_lshlrev_b32_e32 v224, 16, v225
	v_add_f32_dpp v200, v200, v200 row_half_mirror row_mask:0xf bank_mask:0xf bound_ctrl:1
	v_and_b32_e32 v225, 0xffff0000, v225
	s_nop 0
	v_add_f32_dpp v200, v200, v200 row_mirror row_mask:0xf bank_mask:0xf bound_ctrl:1
	v_mul_f32_e32 v200, 0x3c800000, v200
	v_pk_add_f32 v[220:221], v[220:221], v[200:201] op_sel_hi:[1,0] neg_lo:[0,1] neg_hi:[0,1]
	v_pk_add_f32 v[218:219], v[218:219], v[200:201] op_sel_hi:[1,0] neg_lo:[0,1] neg_hi:[0,1]
	v_pk_mul_f32 v[226:227], v[220:221], v[220:221]
	v_pk_mul_f32 v[228:229], v[218:219], v[218:219]
	v_add_f32_e32 v200, v226, v227
	v_add_f32_e32 v200, v228, v200
	v_add_f32_e32 v200, v229, v200
	s_nop 1
	v_add_f32_dpp v200, v200, v200 quad_perm:[1,0,3,2] row_mask:0xf bank_mask:0xf bound_ctrl:1
	s_nop 1
	v_add_f32_dpp v200, v200, v200 quad_perm:[2,3,0,1] row_mask:0xf bank_mask:0xf bound_ctrl:1
	s_nop 1
	v_add_f32_dpp v200, v200, v200 row_half_mirror row_mask:0xf bank_mask:0xf bound_ctrl:1
	s_nop 1
	v_add_f32_dpp v200, v200, v200 row_mirror row_mask:0xf bank_mask:0xf bound_ctrl:1
	v_fmamk_f32 v200, v200, 0x3c800000, v6
	v_mul_f32_e32 v207, 0x4b800000, v200
	v_cmp_gt_f32_e32 vcc, s16, v200
	s_nop 1
	v_cndmask_b32_e32 v200, v200, v207, vcc
	v_rsq_f32_e32 v200, v200
	s_nop 0
	v_mul_f32_e32 v207, 0x45800000, v200
	v_cndmask_b32_e32 v200, v200, v207, vcc
	v_pk_mul_f32 v[220:221], v[220:221], v[200:201] op_sel_hi:[1,0]
	v_pk_mul_f32 v[218:219], v[218:219], v[200:201] op_sel_hi:[1,0]
	v_pk_fma_f32 v[208:209], v[208:209], v[220:221], v[212:213]
	v_pk_fma_f32 v[210:211], v[210:211], v[218:219], v[214:215]
	v_pk_add_f32 v[208:209], v[208:209], v[230:231]
	v_pk_add_f32 v[210:211], v[210:211], v[222:223]
	v_pk_mul_f32 v[208:209], v[208:209], v[232:233]
	v_pk_mul_f32 v[210:211], v[210:211], v[224:225]
	v_cvt_pk_bf16_f32 v208, v208, v209
	v_cvt_pk_bf16_f32 v209, v210, v211
	global_store_dwordx2 v[216:217], v[208:209], off
	s_andn2_b64 exec, exec, s[14:15]
	s_cbranch_execnz .LBB0_554
